# scanner: the next chunk's LDS base addresses are computed before the chunk barrier
# speedup vs baseline: 1.0066x; 1.0066x over previous
.LBB0_783:
	s_or_b64 exec, exec, s[10:11]
	v_cmp_gt_u32_e32 vcc, 64, v31
	v_cmp_eq_u32_e64 s[10:11], s4, v32
	s_or_b64 s[26:27], vcc, s[10:11]
	s_and_saveexec_b64 s[10:11], s[26:27]
	s_setprio 3
	s_or_b64 exec, exec, s[10:11]
	s_lshl_b32 s0, s94, 9
	s_and_b32 s0, s0, 0x3000
	s_mulk_i32 s0, 0x4200
	s_add_u32 s0, s24, s0
	s_addc_u32 s1, s25, 0
	s_lshl_b32 s4, s93, 8
	s_and_b32 s4, s4, 0x700
	s_add_u32 s4, s0, s4
	s_addc_u32 s5, s1, 0
	s_ashr_i32 s0, s93, 2
	s_and_b32 s30, s0, -8
	s_ashr_i32 s31, s30, 31
	s_lshl_b64 s[0:1], s[30:31], 2
	s_add_u32 s0, s4, s0
	v_cndmask_b32_e64 v28, 4, 0, vcc
	s_addc_u32 s1, s5, s1
	v_lshrrev_b32_e32 v29, 4, v30
	s_add_u32 s28, s0, 0x33f1800
	v_and_b32_e32 v32, 15, v31
	v_or_b32_e32 v95, v28, v29
	s_addc_u32 s29, s1, 0
	v_lshlrev_b32_e32 v28, 6, v95
	s_add_i32 s1, 0, 0x18000
	v_lshlrev_b32_e32 v29, 2, v32
	v_add3_u32 v102, s1, v28, v29
	v_mul_lo_u32 v28, v34, 56
	v_sub_u32_e32 v28, v144, v28
	v_cmp_lt_u32_e64 s[10:11], 15, v28
	v_lshlrev_b32_e32 v29, 3, v28
	v_lshlrev_b32_e32 v105, 4, v28
	v_add_u32_e32 v28, 0x100, v144
	v_lshlrev_b32_e32 v97, 4, v32
	v_and_b32_e32 v32, 56, v29
	v_and_b32_e32 v104, 0x1c0, v29
	v_lshrrev_b32_e32 v29, 3, v28
	v_mul_hi_u32 v29, v29, s51
	v_mul_lo_u32 v103, v34, s52
	v_mul_lo_u32 v34, v29, 56
	v_sub_u32_e32 v28, v28, v34
	v_cmp_lt_u32_e64 s[12:13], 15, v28
	v_lshlrev_b32_e32 v34, 3, v28
	v_lshlrev_b32_e32 v108, 4, v28
	v_add_u32_e32 v28, 0x200, v144
	v_mul_lo_u32 v106, v29, s52
	v_lshrrev_b32_e32 v29, 3, v28
	v_mul_hi_u32 v29, v29, s51
	v_and_b32_e32 v35, 56, v34
	v_and_b32_e32 v107, 0x1c0, v34
	v_mul_lo_u32 v34, v29, 56
	v_sub_u32_e32 v28, v28, v34
	v_cmp_lt_u32_e64 s[14:15], 15, v28
	v_lshlrev_b32_e32 v34, 3, v28
	v_lshlrev_b32_e32 v111, 4, v28
	v_add_u32_e32 v28, 0x300, v144
	v_mul_lo_u32 v109, v29, s52
	v_lshrrev_b32_e32 v29, 3, v28
	v_mul_hi_u32 v29, v29, s51
	v_and_b32_e32 v36, 56, v34
	v_and_b32_e32 v110, 0x1c0, v34
	v_mul_lo_u32 v34, v29, 56
	v_sub_u32_e32 v28, v28, v34
	v_cmp_lt_u32_e64 s[16:17], 15, v28
	v_lshlrev_b32_e32 v34, 3, v28
	v_lshlrev_b32_e32 v114, 4, v28
	v_add_u32_e32 v28, 0x400, v144
	v_mul_lo_u32 v112, v29, s52
	v_lshrrev_b32_e32 v29, 3, v28
	v_mul_hi_u32 v29, v29, s51
	v_and_b32_e32 v37, 56, v34
	v_and_b32_e32 v113, 0x1c0, v34
	v_mul_lo_u32 v34, v29, 56
	v_sub_u32_e32 v28, v28, v34
	v_cmp_lt_u32_e64 s[18:19], 15, v28
	v_lshlrev_b32_e32 v34, 3, v28
	v_lshlrev_b32_e32 v117, 4, v28
	v_add_u32_e32 v28, 0x500, v144
	v_mul_lo_u32 v115, v29, s52
	v_lshrrev_b32_e32 v29, 3, v28
	v_mul_hi_u32 v29, v29, s51
	v_and_b32_e32 v38, 56, v34
	v_and_b32_e32 v116, 0x1c0, v34
	v_mul_lo_u32 v34, v29, 56
	v_sub_u32_e32 v28, v28, v34
	v_cmp_lt_u32_e64 s[20:21], 15, v28
	v_lshlrev_b32_e32 v34, 3, v28
	v_lshlrev_b32_e32 v120, 4, v28
	v_add_u32_e32 v28, 0x600, v144
	v_mul_lo_u32 v118, v29, s52
	v_lshrrev_b32_e32 v29, 3, v28
	s_and_b32 s0, s48, 31
	v_mul_hi_u32 v29, v29, s51
	s_mul_i32 s0, s0, 0x380000
	v_and_b32_e32 v39, 56, v34
	v_and_b32_e32 v119, 0x1c0, v34
	v_mul_lo_u32 v34, v29, 56
	v_and_b32_e32 v88, 7, v31
	v_sub_u32_e32 v28, v28, v34
	v_lshlrev_b32_e32 v121, 6, v144
	v_lshlrev_b32_e32 v144, 2, v88
	s_add_u32 s0, s24, s0
	v_lshlrev_b32_e32 v34, 3, v28
	v_add_u32_e32 v125, s1, v121
	v_lshl_add_u64 v[90:91], s[28:29], 0, v[144:145]
	v_add_u32_e32 v144, v33, v30
	s_addc_u32 s1, s25, 0
	v_cmp_lt_u32_e64 s[22:23], 15, v28
	v_and_b32_e32 v40, 56, v34
	v_lshlrev_b32_e32 v124, 4, v28
	v_lshrrev_b32_e32 v28, 3, v144
	v_lshl_add_u64 v[92:93], v[144:145], 4, s[0:1]
	v_mov_b32_e32 v144, v145
	s_mov_b32 s54, 0
	v_mul_lo_u32 v122, v29, s52
	v_and_b32_e32 v123, 0x1c0, v34
	v_subrev_u32_e32 v126, 35, v28
	s_movk_i32 s31, 0xf000
	s_mov_b64 s[34:35], 0
	v_lshlrev_b32_e32 v127, 2, v32
	v_lshlrev_b32_e32 v128, 2, v35
	v_lshlrev_b32_e32 v129, 2, v36
	v_lshlrev_b32_e32 v130, 2, v37
	v_lshlrev_b32_e32 v131, 2, v38
	v_lshlrev_b32_e32 v132, 2, v39
	v_lshlrev_b32_e32 v133, 2, v40
	v_mov_b64_e32 v[32:33], v[144:145]
	v_mov_b64_e32 v[34:35], v[144:145]
	s_and_saveexec_b64 s[0:1], s[26:27]
	s_cbranch_execz .Lscan_init_done
	v_mov_b32_e32 v0, 0
	v_mov_b32_e32 v1, 0
	v_mov_b32_e32 v2, 0
	v_mov_b32_e32 v3, 0
	v_mov_b32_e32 v4, 0
	v_mov_b32_e32 v5, 0
	v_mov_b32_e32 v6, 0
	v_mov_b32_e32 v7, 0
	v_mov_b32_e32 v8, 0
	v_mov_b32_e32 v9, 0
	v_mov_b32_e32 v14, 0
	v_mov_b32_e32 v15, 0
	v_mov_b32_e32 v16, 0
	v_mov_b32_e32 v17, 0
	v_mov_b32_e32 v48, 0
	v_mov_b32_e32 v49, 0
	v_mov_b32_e32 v50, 0
	v_mov_b32_e32 v51, 0
	v_mov_b32_e32 v52, 0
	v_mov_b32_e32 v53, 0
	v_mov_b32_e32 v54, 0
	v_mov_b32_e32 v55, 0
	v_mov_b32_e32 v56, 0
	v_mov_b32_e32 v57, 0
	v_mov_b32_e32 v58, 0
	v_mov_b32_e32 v59, 0
	v_mov_b32_e32 v60, 0
	v_mov_b32_e32 v61, 0
	v_mov_b32_e32 v62, 0
	v_mov_b32_e32 v63, 0
	v_mov_b32_e32 v64, 0
	v_mov_b32_e32 v65, 0
	v_mov_b32_e32 v66, 0
	v_mov_b32_e32 v67, 0
	v_mov_b32_e32 v68, 0
	v_mov_b32_e32 v69, 0
	v_mov_b32_e32 v70, 0
	v_mov_b32_e32 v71, 0
	v_mov_b32_e32 v72, 0
	v_mov_b32_e32 v73, 0
	v_mov_b32_e32 v74, 0
	v_mov_b32_e32 v75, 0
	v_mov_b32_e32 v76, 0
	v_mov_b32_e32 v77, 0
	v_mov_b32_e32 v78, 0
	v_mov_b32_e32 v79, 0
	v_mov_b32_e32 v80, 0
	v_mov_b32_e32 v81, 0
	v_mov_b32_e32 v82, 0
	v_mov_b32_e32 v83, 0
	v_mov_b32_e32 v84, 0
	v_mov_b32_e32 v85, 0
	v_mov_b32_e32 v86, 0
	v_mov_b32_e32 v87, 0
	v_mov_b32_e32 v104, 0
	v_mov_b32_e32 v105, 0
	v_mov_b32_e32 v106, 0
	v_mov_b32_e32 v107, 0
	v_mov_b32_e32 v108, 0
	v_mov_b32_e32 v109, 0
	v_mov_b32_e32 v110, 0
	v_mov_b32_e32 v111, 0
	v_mov_b32_e32 v112, 0
	v_mov_b32_e32 v113, 0
	v_mov_b32_e32 v114, 0
	v_mov_b32_e32 v115, 0
	v_mov_b32_e32 v116, 0
	v_mov_b32_e32 v117, 0
	v_mov_b32_e32 v118, 0
	v_mov_b32_e32 v119, 0
	v_mov_b32_e32 v120, 0
	v_mov_b32_e32 v121, 0
	v_mov_b32_e32 v122, 0
	v_mov_b32_e32 v123, 0
	s_lshl_b32 s4, s30, 2
	v_mov_b32_e32 v10, v97
	v_lshl_add_u32 v11, v95, 2, s4
	v_mov_b32_e32 v12, v102

.LBB0_787:
	s_and_saveexec_b64 s[0:1], s[8:9]
	s_xor_b64 s[36:37], exec, s[0:1]
	s_cbranch_execz .LBB0_791
	s_and_saveexec_b64 s[44:45], s[26:27]
	s_cbranch_execz .LBB0_790
	v_pk_fma_f32 v[4:5], v[60:61], v[64:65], v[56:57] op_sel_hi:[0,1,1]
	v_pk_fma_f32 v[6:7], v[60:61], v[66:67], v[58:59] op_sel_hi:[0,1,1]
	v_pk_mul_f32 v[80:81], v[4:5], v[80:81]
	v_pk_fma_f32 v[80:81], v[6:7], v[82:83], v[80:81]
	v_add_f32_e32 v80, v80, v81
	v_pk_mul_f32 v[76:77], v[76:77], v[2:3] op_sel_hi:[1,0]
	v_pk_mul_f32 v[78:79], v[78:79], v[2:3] op_sel_hi:[1,0]
	v_add_f32_dpp v80, v80, v80 quad_perm:[1,0,3,2] row_mask:0xf bank_mask:0xf bound_ctrl:1
	v_pk_fma_f32 v[76:77], v[4:5], v[68:69], v[76:77]
	v_pk_fma_f32 v[78:79], v[6:7], v[70:71], v[78:79]
	v_add_f32_dpp v80, v80, v80 quad_perm:[2,3,0,1] row_mask:0xf bank_mask:0xf bound_ctrl:1
	v_pk_mul_f32 v[52:53], v[52:53], v[4:5]
	v_pk_fma_f32 v[52:53], v[6:7], v[54:55], v[52:53]
	v_add_f32_dpp v80, v80, v80 row_half_mirror row_mask:0xf bank_mask:0xf bound_ctrl:1
	v_add_f32_e32 v9, v52, v53
	ds_read_b128 v[36:39], v10 offset:512
	ds_read2st64_b32 v[0:1], v11 offset0:5 offset1:11
	ds_read_b128 v[40:43], v10 offset:768
	ds_read_b128 v[28:31], v10 offset:0
	ds_read_b128 v[44:47], v10 offset:1024
	ds_read_b128 v[32:35], v10 offset:256
	ds_read_b128 v[56:59], v10 offset:2048
	ds_read_b128 v[60:63], v10 offset:2304
	ds_read_b128 v[48:51], v10 offset:1536
	ds_read_b128 v[64:67], v10 offset:2560
	ds_read_b128 v[52:55], v10 offset:1792
	v_add_f32_dpp v80, v80, v80 row_mirror row_mask:0xf bank_mask:0xf bound_ctrl:1
	v_pk_fma_f32 v[4:5], v[80:81], v[84:85], v[76:77] op_sel_hi:[0,1,1]
	v_pk_fma_f32 v[6:7], v[80:81], v[86:87], v[78:79] op_sel_hi:[0,1,1]
	v_pk_mul_f32 v[116:117], v[4:5], v[116:117]
	v_pk_fma_f32 v[116:117], v[6:7], v[118:119], v[116:117]
	v_add_f32_e32 v116, v116, v117
	v_pk_mul_f32 v[112:113], v[112:113], v[2:3] op_sel:[0,1] op_sel_hi:[1,1]
	v_pk_mul_f32 v[114:115], v[114:115], v[2:3] op_sel:[0,1] op_sel_hi:[1,1]
	v_add_f32_dpp v116, v116, v116 quad_perm:[1,0,3,2] row_mask:0xf bank_mask:0xf bound_ctrl:1
	v_pk_fma_f32 v[112:113], v[4:5], v[104:105], v[112:113]
	v_pk_fma_f32 v[114:115], v[6:7], v[106:107], v[114:115]
	v_add_f32_dpp v116, v116, v116 quad_perm:[2,3,0,1] row_mask:0xf bank_mask:0xf bound_ctrl:1
	v_pk_mul_f32 v[72:73], v[72:73], v[4:5]
	v_pk_fma_f32 v[72:73], v[6:7], v[74:75], v[72:73]
	v_add_f32_dpp v116, v116, v116 row_half_mirror row_mask:0xf bank_mask:0xf bound_ctrl:1
	v_add_f32_e32 v8, v72, v73
	ds_read_b128 v[76:79], v10 offset:3584
	ds_read2st64_b32 v[2:3], v11 offset0:17 offset1:23
	ds_read_b128 v[80:83], v10 offset:3840
	ds_read_b128 v[68:71], v10 offset:3072
	ds_read_b128 v[84:87], v10 offset:4096
	ds_read_b128 v[72:75], v10 offset:3328
	ds_write2st64_b32 v12, v9, v8 offset0:0 offset1:2
	v_add_f32_dpp v116, v116, v116 row_mirror row_mask:0xf bank_mask:0xf bound_ctrl:1
	v_pk_fma_f32 v[4:5], v[116:117], v[120:121], v[112:113] op_sel_hi:[0,1,1]
	v_pk_fma_f32 v[6:7], v[116:117], v[122:123], v[114:115] op_sel_hi:[0,1,1]
	s_waitcnt lgkmcnt(12)
	v_pk_mul_f32 v[40:41], v[4:5], v[40:41]
	v_pk_fma_f32 v[40:41], v[6:7], v[42:43], v[40:41]
	v_add_f32_e32 v40, v40, v41
	v_pk_mul_f32 v[36:37], v[36:37], v[0:1] op_sel_hi:[1,0]
	v_pk_mul_f32 v[38:39], v[38:39], v[0:1] op_sel_hi:[1,0]
	v_add_f32_dpp v40, v40, v40 quad_perm:[1,0,3,2] row_mask:0xf bank_mask:0xf bound_ctrl:1
	v_pk_fma_f32 v[36:37], v[4:5], v[28:29], v[36:37]
	v_pk_fma_f32 v[38:39], v[6:7], v[30:31], v[38:39]
	v_add_f32_dpp v40, v40, v40 quad_perm:[2,3,0,1] row_mask:0xf bank_mask:0xf bound_ctrl:1
	v_pk_mul_f32 v[108:109], v[108:109], v[4:5]
	v_pk_fma_f32 v[108:109], v[6:7], v[110:111], v[108:109]
	v_add_f32_dpp v40, v40, v40 row_half_mirror row_mask:0xf bank_mask:0xf bound_ctrl:1
	v_add_f32_e32 v9, v108, v109
	ds_read_b128 v[112:115], v10 offset:5120
	ds_read_b128 v[116:119], v10 offset:5376
	ds_read_b128 v[104:107], v10 offset:4608
	ds_read_b128 v[120:123], v10 offset:5632
	ds_read_b128 v[108:111], v10 offset:4864
	v_add_f32_dpp v40, v40, v40 row_mirror row_mask:0xf bank_mask:0xf bound_ctrl:1
	v_pk_fma_f32 v[4:5], v[40:41], v[44:45], v[36:37] op_sel_hi:[0,1,1]
	v_pk_fma_f32 v[6:7], v[40:41], v[46:47], v[38:39] op_sel_hi:[0,1,1]
	s_waitcnt lgkmcnt(12)
	v_pk_mul_f32 v[60:61], v[4:5], v[60:61]
	v_pk_fma_f32 v[60:61], v[6:7], v[62:63], v[60:61]
	v_add_f32_e32 v60, v60, v61
	v_pk_mul_f32 v[56:57], v[56:57], v[0:1] op_sel:[0,1] op_sel_hi:[1,1]
	v_pk_mul_f32 v[58:59], v[58:59], v[0:1] op_sel:[0,1] op_sel_hi:[1,1]
	v_add_f32_dpp v60, v60, v60 quad_perm:[1,0,3,2] row_mask:0xf bank_mask:0xf bound_ctrl:1
	v_pk_fma_f32 v[56:57], v[4:5], v[48:49], v[56:57]
	v_pk_fma_f32 v[58:59], v[6:7], v[50:51], v[58:59]
	v_add_f32_dpp v60, v60, v60 quad_perm:[2,3,0,1] row_mask:0xf bank_mask:0xf bound_ctrl:1
	v_pk_mul_f32 v[32:33], v[32:33], v[4:5]
	v_pk_fma_f32 v[32:33], v[6:7], v[34:35], v[32:33]
	v_add_f32_dpp v60, v60, v60 row_half_mirror row_mask:0xf bank_mask:0xf bound_ctrl:1
	v_add_f32_e32 v8, v32, v33
	ds_read_b128 v[36:39], v10 offset:6656
	ds_read2st64_b32 v[0:1], v11 offset0:29 offset1:35
	ds_read_b128 v[40:43], v10 offset:6912
	ds_read_b128 v[28:31], v10 offset:6144
	ds_read_b128 v[44:47], v10 offset:7168
	ds_read_b128 v[32:35], v10 offset:6400
	ds_write2st64_b32 v12, v9, v8 offset0:4 offset1:6
	v_add_f32_dpp v60, v60, v60 row_mirror row_mask:0xf bank_mask:0xf bound_ctrl:1
	v_pk_fma_f32 v[4:5], v[60:61], v[64:65], v[56:57] op_sel_hi:[0,1,1]
	v_pk_fma_f32 v[6:7], v[60:61], v[66:67], v[58:59] op_sel_hi:[0,1,1]
	s_waitcnt lgkmcnt(13)
	v_pk_mul_f32 v[80:81], v[4:5], v[80:81]
	v_pk_fma_f32 v[80:81], v[6:7], v[82:83], v[80:81]
	v_add_f32_e32 v80, v80, v81
	v_pk_mul_f32 v[76:77], v[76:77], v[2:3] op_sel_hi:[1,0]
	v_pk_mul_f32 v[78:79], v[78:79], v[2:3] op_sel_hi:[1,0]
	v_add_f32_dpp v80, v80, v80 quad_perm:[1,0,3,2] row_mask:0xf bank_mask:0xf bound_ctrl:1
	v_pk_fma_f32 v[76:77], v[4:5], v[68:69], v[76:77]
	v_pk_fma_f32 v[78:79], v[6:7], v[70:71], v[78:79]
	v_add_f32_dpp v80, v80, v80 quad_perm:[2,3,0,1] row_mask:0xf bank_mask:0xf bound_ctrl:1
	v_pk_mul_f32 v[52:53], v[52:53], v[4:5]
	v_pk_fma_f32 v[52:53], v[6:7], v[54:55], v[52:53]
	v_add_f32_dpp v80, v80, v80 row_half_mirror row_mask:0xf bank_mask:0xf bound_ctrl:1
	v_add_f32_e32 v9, v52, v53
	ds_read_b128 v[56:59], v10 offset:8192
	ds_read_b128 v[60:63], v10 offset:8448
	ds_read_b128 v[48:51], v10 offset:7680
	ds_read_b128 v[64:67], v10 offset:8704
	ds_read_b128 v[52:55], v10 offset:7936
	v_add_f32_dpp v80, v80, v80 row_mirror row_mask:0xf bank_mask:0xf bound_ctrl:1
	v_pk_fma_f32 v[4:5], v[80:81], v[84:85], v[76:77] op_sel_hi:[0,1,1]
	v_pk_fma_f32 v[6:7], v[80:81], v[86:87], v[78:79] op_sel_hi:[0,1,1]
	s_waitcnt lgkmcnt(12)
	v_pk_mul_f32 v[116:117], v[4:5], v[116:117]
	v_pk_fma_f32 v[116:117], v[6:7], v[118:119], v[116:117]
	v_add_f32_e32 v116, v116, v117
	v_pk_mul_f32 v[112:113], v[112:113], v[2:3] op_sel:[0,1] op_sel_hi:[1,1]
	v_pk_mul_f32 v[114:115], v[114:115], v[2:3] op_sel:[0,1] op_sel_hi:[1,1]
	v_add_f32_dpp v116, v116, v116 quad_perm:[1,0,3,2] row_mask:0xf bank_mask:0xf bound_ctrl:1
	v_pk_fma_f32 v[112:113], v[4:5], v[104:105], v[112:113]
	v_pk_fma_f32 v[114:115], v[6:7], v[106:107], v[114:115]
	v_add_f32_dpp v116, v116, v116 quad_perm:[2,3,0,1] row_mask:0xf bank_mask:0xf bound_ctrl:1
	v_pk_mul_f32 v[72:73], v[72:73], v[4:5]
	v_pk_fma_f32 v[72:73], v[6:7], v[74:75], v[72:73]
	v_add_f32_dpp v116, v116, v116 row_half_mirror row_mask:0xf bank_mask:0xf bound_ctrl:1
	v_add_f32_e32 v8, v72, v73
	ds_read_b128 v[76:79], v10 offset:9728
	ds_read2st64_b32 v[2:3], v11 offset0:41 offset1:47
	ds_read_b128 v[80:83], v10 offset:9984
	ds_read_b128 v[68:71], v10 offset:9216
	ds_read_b128 v[84:87], v10 offset:10240
	ds_read_b128 v[72:75], v10 offset:9472
	ds_write2st64_b32 v12, v9, v8 offset0:8 offset1:10
	v_add_f32_dpp v116, v116, v116 row_mirror row_mask:0xf bank_mask:0xf bound_ctrl:1
	v_pk_fma_f32 v[4:5], v[116:117], v[120:121], v[112:113] op_sel_hi:[0,1,1]
	v_pk_fma_f32 v[6:7], v[116:117], v[122:123], v[114:115] op_sel_hi:[0,1,1]
	s_waitcnt lgkmcnt(13)
	v_pk_mul_f32 v[40:41], v[4:5], v[40:41]
	v_pk_fma_f32 v[40:41], v[6:7], v[42:43], v[40:41]
	v_add_f32_e32 v40, v40, v41
	v_pk_mul_f32 v[36:37], v[36:37], v[0:1] op_sel_hi:[1,0]
	v_pk_mul_f32 v[38:39], v[38:39], v[0:1] op_sel_hi:[1,0]
	v_add_f32_dpp v40, v40, v40 quad_perm:[1,0,3,2] row_mask:0xf bank_mask:0xf bound_ctrl:1
	v_pk_fma_f32 v[36:37], v[4:5], v[28:29], v[36:37]
	v_pk_fma_f32 v[38:39], v[6:7], v[30:31], v[38:39]
	v_add_f32_dpp v40, v40, v40 quad_perm:[2,3,0,1] row_mask:0xf bank_mask:0xf bound_ctrl:1
	v_pk_mul_f32 v[108:109], v[108:109], v[4:5]
	v_pk_fma_f32 v[108:109], v[6:7], v[110:111], v[108:109]
	v_add_f32_dpp v40, v40, v40 row_half_mirror row_mask:0xf bank_mask:0xf bound_ctrl:1
	v_add_f32_e32 v9, v108, v109
	ds_read_b128 v[112:115], v10 offset:11264
	ds_read_b128 v[116:119], v10 offset:11520
	ds_read_b128 v[104:107], v10 offset:10752
	ds_read_b128 v[120:123], v10 offset:11776
	ds_read_b128 v[108:111], v10 offset:11008
	v_add_f32_dpp v40, v40, v40 row_mirror row_mask:0xf bank_mask:0xf bound_ctrl:1
	v_pk_fma_f32 v[4:5], v[40:41], v[44:45], v[36:37] op_sel_hi:[0,1,1]
	v_pk_fma_f32 v[6:7], v[40:41], v[46:47], v[38:39] op_sel_hi:[0,1,1]
	s_waitcnt lgkmcnt(12)
	v_pk_mul_f32 v[60:61], v[4:5], v[60:61]
	v_pk_fma_f32 v[60:61], v[6:7], v[62:63], v[60:61]
	v_add_f32_e32 v60, v60, v61
	v_pk_mul_f32 v[56:57], v[56:57], v[0:1] op_sel:[0,1] op_sel_hi:[1,1]
	v_pk_mul_f32 v[58:59], v[58:59], v[0:1] op_sel:[0,1] op_sel_hi:[1,1]
	v_add_f32_dpp v60, v60, v60 quad_perm:[1,0,3,2] row_mask:0xf bank_mask:0xf bound_ctrl:1
	v_pk_fma_f32 v[56:57], v[4:5], v[48:49], v[56:57]
	v_pk_fma_f32 v[58:59], v[6:7], v[50:51], v[58:59]
	v_add_f32_dpp v60, v60, v60 quad_perm:[2,3,0,1] row_mask:0xf bank_mask:0xf bound_ctrl:1
	v_pk_mul_f32 v[32:33], v[32:33], v[4:5]
	v_pk_fma_f32 v[32:33], v[6:7], v[34:35], v[32:33]
	v_add_f32_dpp v60, v60, v60 row_half_mirror row_mask:0xf bank_mask:0xf bound_ctrl:1
	v_add_f32_e32 v8, v32, v33
	ds_read_b128 v[36:39], v10 offset:12800
	ds_read2st64_b32 v[0:1], v11 offset0:53 offset1:59
	ds_read_b128 v[40:43], v10 offset:13056
	ds_read_b128 v[28:31], v10 offset:12288
	ds_read_b128 v[44:47], v10 offset:13312
	ds_read_b128 v[32:35], v10 offset:12544
	ds_write2st64_b32 v12, v9, v8 offset0:12 offset1:14
	v_add_f32_dpp v60, v60, v60 row_mirror row_mask:0xf bank_mask:0xf bound_ctrl:1
	v_pk_fma_f32 v[4:5], v[60:61], v[64:65], v[56:57] op_sel_hi:[0,1,1]
	v_pk_fma_f32 v[6:7], v[60:61], v[66:67], v[58:59] op_sel_hi:[0,1,1]
	s_waitcnt lgkmcnt(13)
	v_pk_mul_f32 v[80:81], v[4:5], v[80:81]
	v_pk_fma_f32 v[80:81], v[6:7], v[82:83], v[80:81]
	v_add_f32_e32 v80, v80, v81
	v_pk_mul_f32 v[76:77], v[76:77], v[2:3] op_sel_hi:[1,0]
	v_pk_mul_f32 v[78:79], v[78:79], v[2:3] op_sel_hi:[1,0]
	v_add_f32_dpp v80, v80, v80 quad_perm:[1,0,3,2] row_mask:0xf bank_mask:0xf bound_ctrl:1
	v_pk_fma_f32 v[76:77], v[4:5], v[68:69], v[76:77]
	v_pk_fma_f32 v[78:79], v[6:7], v[70:71], v[78:79]
	v_add_f32_dpp v80, v80, v80 quad_perm:[2,3,0,1] row_mask:0xf bank_mask:0xf bound_ctrl:1
	v_pk_mul_f32 v[52:53], v[52:53], v[4:5]
	v_pk_fma_f32 v[52:53], v[6:7], v[54:55], v[52:53]
	v_add_f32_dpp v80, v80, v80 row_half_mirror row_mask:0xf bank_mask:0xf bound_ctrl:1
	v_add_f32_e32 v9, v52, v53
	ds_read_b128 v[56:59], v10 offset:14336
	ds_read_b128 v[60:63], v10 offset:14592
	ds_read_b128 v[48:51], v10 offset:13824
	ds_read_b128 v[64:67], v10 offset:14848
	ds_read_b128 v[52:55], v10 offset:14080
	v_add_f32_dpp v80, v80, v80 row_mirror row_mask:0xf bank_mask:0xf bound_ctrl:1
	v_pk_fma_f32 v[4:5], v[80:81], v[84:85], v[76:77] op_sel_hi:[0,1,1]
	v_pk_fma_f32 v[6:7], v[80:81], v[86:87], v[78:79] op_sel_hi:[0,1,1]
	s_waitcnt lgkmcnt(12)
	v_pk_mul_f32 v[116:117], v[4:5], v[116:117]
	v_pk_fma_f32 v[116:117], v[6:7], v[118:119], v[116:117]
	v_add_f32_e32 v116, v116, v117
	v_pk_mul_f32 v[112:113], v[112:113], v[2:3] op_sel:[0,1] op_sel_hi:[1,1]
	v_pk_mul_f32 v[114:115], v[114:115], v[2:3] op_sel:[0,1] op_sel_hi:[1,1]
	v_add_f32_dpp v116, v116, v116 quad_perm:[1,0,3,2] row_mask:0xf bank_mask:0xf bound_ctrl:1
	v_pk_fma_f32 v[112:113], v[4:5], v[104:105], v[112:113]
	v_pk_fma_f32 v[114:115], v[6:7], v[106:107], v[114:115]
	v_add_f32_dpp v116, v116, v116 quad_perm:[2,3,0,1] row_mask:0xf bank_mask:0xf bound_ctrl:1
	v_pk_mul_f32 v[72:73], v[72:73], v[4:5]
	v_pk_fma_f32 v[72:73], v[6:7], v[74:75], v[72:73]
	v_add_f32_dpp v116, v116, v116 row_half_mirror row_mask:0xf bank_mask:0xf bound_ctrl:1
	v_add_f32_e32 v8, v72, v73
	ds_read_b128 v[76:79], v10 offset:15872
	ds_read2st64_b32 v[2:3], v11 offset0:65 offset1:71
	ds_read_b128 v[80:83], v10 offset:16128
	ds_read_b128 v[68:71], v10 offset:15360
	ds_read_b128 v[84:87], v10 offset:16384
	ds_read_b128 v[72:75], v10 offset:15616
	ds_write2st64_b32 v12, v9, v8 offset0:16 offset1:18
	v_add_f32_dpp v116, v116, v116 row_mirror row_mask:0xf bank_mask:0xf bound_ctrl:1
	v_pk_fma_f32 v[4:5], v[116:117], v[120:121], v[112:113] op_sel_hi:[0,1,1]
	v_pk_fma_f32 v[6:7], v[116:117], v[122:123], v[114:115] op_sel_hi:[0,1,1]
	s_waitcnt lgkmcnt(13)
	v_pk_mul_f32 v[40:41], v[4:5], v[40:41]
	v_pk_fma_f32 v[40:41], v[6:7], v[42:43], v[40:41]
	v_add_f32_e32 v40, v40, v41
	v_pk_mul_f32 v[36:37], v[36:37], v[0:1] op_sel_hi:[1,0]
	v_pk_mul_f32 v[38:39], v[38:39], v[0:1] op_sel_hi:[1,0]
	v_add_f32_dpp v40, v40, v40 quad_perm:[1,0,3,2] row_mask:0xf bank_mask:0xf bound_ctrl:1
	v_pk_fma_f32 v[36:37], v[4:5], v[28:29], v[36:37]
	v_pk_fma_f32 v[38:39], v[6:7], v[30:31], v[38:39]
	v_add_f32_dpp v40, v40, v40 quad_perm:[2,3,0,1] row_mask:0xf bank_mask:0xf bound_ctrl:1
	v_pk_mul_f32 v[108:109], v[108:109], v[4:5]
	v_pk_fma_f32 v[108:109], v[6:7], v[110:111], v[108:109]
	v_add_f32_dpp v40, v40, v40 row_half_mirror row_mask:0xf bank_mask:0xf bound_ctrl:1
	v_add_f32_e32 v9, v108, v109
	ds_read_b128 v[112:115], v10 offset:17408
	ds_read_b128 v[116:119], v10 offset:17664
	ds_read_b128 v[104:107], v10 offset:16896
	ds_read_b128 v[120:123], v10 offset:17920
	ds_read_b128 v[108:111], v10 offset:17152
	v_add_f32_dpp v40, v40, v40 row_mirror row_mask:0xf bank_mask:0xf bound_ctrl:1
	v_pk_fma_f32 v[4:5], v[40:41], v[44:45], v[36:37] op_sel_hi:[0,1,1]
	v_pk_fma_f32 v[6:7], v[40:41], v[46:47], v[38:39] op_sel_hi:[0,1,1]
	s_waitcnt lgkmcnt(12)
	v_pk_mul_f32 v[60:61], v[4:5], v[60:61]
	v_pk_fma_f32 v[60:61], v[6:7], v[62:63], v[60:61]
	v_add_f32_e32 v60, v60, v61
	v_pk_mul_f32 v[56:57], v[56:57], v[0:1] op_sel:[0,1] op_sel_hi:[1,1]
	v_pk_mul_f32 v[58:59], v[58:59], v[0:1] op_sel:[0,1] op_sel_hi:[1,1]
	v_add_f32_dpp v60, v60, v60 quad_perm:[1,0,3,2] row_mask:0xf bank_mask:0xf bound_ctrl:1
	v_pk_fma_f32 v[56:57], v[4:5], v[48:49], v[56:57]
	v_pk_fma_f32 v[58:59], v[6:7], v[50:51], v[58:59]
	v_add_f32_dpp v60, v60, v60 quad_perm:[2,3,0,1] row_mask:0xf bank_mask:0xf bound_ctrl:1
	v_pk_mul_f32 v[32:33], v[32:33], v[4:5]
	v_pk_fma_f32 v[32:33], v[6:7], v[34:35], v[32:33]
	v_add_f32_dpp v60, v60, v60 row_half_mirror row_mask:0xf bank_mask:0xf bound_ctrl:1
	v_add_f32_e32 v8, v32, v33
	ds_read_b128 v[36:39], v10 offset:18944
	ds_read2st64_b32 v[0:1], v11 offset0:77 offset1:83
	ds_read_b128 v[40:43], v10 offset:19200
	ds_read_b128 v[28:31], v10 offset:18432
	ds_read_b128 v[44:47], v10 offset:19456
	ds_read_b128 v[32:35], v10 offset:18688
	ds_write2st64_b32 v12, v9, v8 offset0:20 offset1:22
	v_add_f32_dpp v60, v60, v60 row_mirror row_mask:0xf bank_mask:0xf bound_ctrl:1
	v_pk_fma_f32 v[4:5], v[60:61], v[64:65], v[56:57] op_sel_hi:[0,1,1]
	v_pk_fma_f32 v[6:7], v[60:61], v[66:67], v[58:59] op_sel_hi:[0,1,1]
	s_waitcnt lgkmcnt(13)
	v_pk_mul_f32 v[80:81], v[4:5], v[80:81]
	v_pk_fma_f32 v[80:81], v[6:7], v[82:83], v[80:81]
	v_add_f32_e32 v80, v80, v81
	v_pk_mul_f32 v[76:77], v[76:77], v[2:3] op_sel_hi:[1,0]
	v_pk_mul_f32 v[78:79], v[78:79], v[2:3] op_sel_hi:[1,0]
	v_add_f32_dpp v80, v80, v80 quad_perm:[1,0,3,2] row_mask:0xf bank_mask:0xf bound_ctrl:1
	v_pk_fma_f32 v[76:77], v[4:5], v[68:69], v[76:77]
	v_pk_fma_f32 v[78:79], v[6:7], v[70:71], v[78:79]
	v_add_f32_dpp v80, v80, v80 quad_perm:[2,3,0,1] row_mask:0xf bank_mask:0xf bound_ctrl:1
	v_pk_mul_f32 v[52:53], v[52:53], v[4:5]
	v_pk_fma_f32 v[52:53], v[6:7], v[54:55], v[52:53]
	v_add_f32_dpp v80, v80, v80 row_half_mirror row_mask:0xf bank_mask:0xf bound_ctrl:1
	v_add_f32_e32 v9, v52, v53
	ds_read_b128 v[56:59], v10 offset:20480
	ds_read_b128 v[60:63], v10 offset:20736
	ds_read_b128 v[48:51], v10 offset:19968
	ds_read_b128 v[64:67], v10 offset:20992
	ds_read_b128 v[52:55], v10 offset:20224
	v_add_f32_dpp v80, v80, v80 row_mirror row_mask:0xf bank_mask:0xf bound_ctrl:1
	v_pk_fma_f32 v[4:5], v[80:81], v[84:85], v[76:77] op_sel_hi:[0,1,1]
	v_pk_fma_f32 v[6:7], v[80:81], v[86:87], v[78:79] op_sel_hi:[0,1,1]
	s_waitcnt lgkmcnt(12)
	v_pk_mul_f32 v[116:117], v[4:5], v[116:117]
	v_pk_fma_f32 v[116:117], v[6:7], v[118:119], v[116:117]
	v_add_f32_e32 v116, v116, v117
	v_pk_mul_f32 v[112:113], v[112:113], v[2:3] op_sel:[0,1] op_sel_hi:[1,1]
	v_pk_mul_f32 v[114:115], v[114:115], v[2:3] op_sel:[0,1] op_sel_hi:[1,1]
	v_add_f32_dpp v116, v116, v116 quad_perm:[1,0,3,2] row_mask:0xf bank_mask:0xf bound_ctrl:1
	v_pk_fma_f32 v[112:113], v[4:5], v[104:105], v[112:113]
	v_pk_fma_f32 v[114:115], v[6:7], v[106:107], v[114:115]
	v_add_f32_dpp v116, v116, v116 quad_perm:[2,3,0,1] row_mask:0xf bank_mask:0xf bound_ctrl:1
	v_pk_mul_f32 v[72:73], v[72:73], v[4:5]
	v_pk_fma_f32 v[72:73], v[6:7], v[74:75], v[72:73]
	v_add_f32_dpp v116, v116, v116 row_half_mirror row_mask:0xf bank_mask:0xf bound_ctrl:1
	v_add_f32_e32 v8, v72, v73
	ds_read_b128 v[76:79], v10 offset:22016
	ds_read2st64_b32 v[2:3], v11 offset0:89 offset1:95
	ds_read_b128 v[80:83], v10 offset:22272
	ds_read_b128 v[68:71], v10 offset:21504
	ds_read_b128 v[84:87], v10 offset:22528
	ds_read_b128 v[72:75], v10 offset:21760
	ds_write2st64_b32 v12, v9, v8 offset0:24 offset1:26
	v_add_f32_dpp v116, v116, v116 row_mirror row_mask:0xf bank_mask:0xf bound_ctrl:1
	v_pk_fma_f32 v[4:5], v[116:117], v[120:121], v[112:113] op_sel_hi:[0,1,1]
	v_pk_fma_f32 v[6:7], v[116:117], v[122:123], v[114:115] op_sel_hi:[0,1,1]
	s_waitcnt lgkmcnt(13)
	v_pk_mul_f32 v[40:41], v[4:5], v[40:41]
	v_pk_fma_f32 v[40:41], v[6:7], v[42:43], v[40:41]
	v_add_f32_e32 v40, v40, v41
	v_pk_mul_f32 v[36:37], v[36:37], v[0:1] op_sel_hi:[1,0]
	v_pk_mul_f32 v[38:39], v[38:39], v[0:1] op_sel_hi:[1,0]
	v_add_f32_dpp v40, v40, v40 quad_perm:[1,0,3,2] row_mask:0xf bank_mask:0xf bound_ctrl:1
	v_pk_fma_f32 v[36:37], v[4:5], v[28:29], v[36:37]
	v_pk_fma_f32 v[38:39], v[6:7], v[30:31], v[38:39]
	v_add_f32_dpp v40, v40, v40 quad_perm:[2,3,0,1] row_mask:0xf bank_mask:0xf bound_ctrl:1
	v_pk_mul_f32 v[108:109], v[108:109], v[4:5]
	v_pk_fma_f32 v[108:109], v[6:7], v[110:111], v[108:109]
	v_add_f32_dpp v40, v40, v40 row_half_mirror row_mask:0xf bank_mask:0xf bound_ctrl:1
	v_add_f32_e32 v9, v108, v109
	ds_read_b128 v[112:115], v10 offset:23552
	ds_read_b128 v[116:119], v10 offset:23808
	ds_read_b128 v[104:107], v10 offset:23040
	ds_read_b128 v[120:123], v10 offset:24064
	ds_read_b128 v[108:111], v10 offset:23296
	v_add_f32_dpp v40, v40, v40 row_mirror row_mask:0xf bank_mask:0xf bound_ctrl:1
	v_pk_fma_f32 v[4:5], v[40:41], v[44:45], v[36:37] op_sel_hi:[0,1,1]
	v_pk_fma_f32 v[6:7], v[40:41], v[46:47], v[38:39] op_sel_hi:[0,1,1]
	s_waitcnt lgkmcnt(12)
	v_pk_mul_f32 v[60:61], v[4:5], v[60:61]
	v_pk_fma_f32 v[60:61], v[6:7], v[62:63], v[60:61]
	v_add_f32_e32 v60, v60, v61
	v_pk_mul_f32 v[56:57], v[56:57], v[0:1] op_sel:[0,1] op_sel_hi:[1,1]
	v_pk_mul_f32 v[58:59], v[58:59], v[0:1] op_sel:[0,1] op_sel_hi:[1,1]
	v_add_f32_dpp v60, v60, v60 quad_perm:[1,0,3,2] row_mask:0xf bank_mask:0xf bound_ctrl:1
	v_pk_fma_f32 v[56:57], v[4:5], v[48:49], v[56:57]
	v_pk_fma_f32 v[58:59], v[6:7], v[50:51], v[58:59]
	v_add_f32_dpp v60, v60, v60 quad_perm:[2,3,0,1] row_mask:0xf bank_mask:0xf bound_ctrl:1
	v_pk_mul_f32 v[32:33], v[32:33], v[4:5]
	v_pk_fma_f32 v[32:33], v[6:7], v[34:35], v[32:33]
	v_add_f32_dpp v60, v60, v60 row_half_mirror row_mask:0xf bank_mask:0xf bound_ctrl:1
	v_add_f32_e32 v8, v32, v33
	ds_read_b128 v[36:39], v10 offset:25088
	ds_read2st64_b32 v[0:1], v11 offset0:101 offset1:107
	ds_read_b128 v[40:43], v10 offset:25344
	ds_read_b128 v[28:31], v10 offset:24576
	ds_read_b128 v[44:47], v10 offset:25600
	ds_read_b128 v[32:35], v10 offset:24832
	ds_write2st64_b32 v12, v9, v8 offset0:28 offset1:30
	v_add_f32_dpp v60, v60, v60 row_mirror row_mask:0xf bank_mask:0xf bound_ctrl:1
	v_pk_fma_f32 v[4:5], v[60:61], v[64:65], v[56:57] op_sel_hi:[0,1,1]
	v_pk_fma_f32 v[6:7], v[60:61], v[66:67], v[58:59] op_sel_hi:[0,1,1]
	s_waitcnt lgkmcnt(13)
	v_pk_mul_f32 v[80:81], v[4:5], v[80:81]
	v_pk_fma_f32 v[80:81], v[6:7], v[82:83], v[80:81]
	v_add_f32_e32 v80, v80, v81
	v_pk_mul_f32 v[76:77], v[76:77], v[2:3] op_sel_hi:[1,0]
	v_pk_mul_f32 v[78:79], v[78:79], v[2:3] op_sel_hi:[1,0]
	v_add_f32_dpp v80, v80, v80 quad_perm:[1,0,3,2] row_mask:0xf bank_mask:0xf bound_ctrl:1
	v_pk_fma_f32 v[76:77], v[4:5], v[68:69], v[76:77]
	v_pk_fma_f32 v[78:79], v[6:7], v[70:71], v[78:79]
	v_add_f32_dpp v80, v80, v80 quad_perm:[2,3,0,1] row_mask:0xf bank_mask:0xf bound_ctrl:1
	v_pk_mul_f32 v[52:53], v[52:53], v[4:5]
	v_pk_fma_f32 v[52:53], v[6:7], v[54:55], v[52:53]
	v_add_f32_dpp v80, v80, v80 row_half_mirror row_mask:0xf bank_mask:0xf bound_ctrl:1
	v_add_f32_e32 v9, v52, v53
	ds_read_b128 v[56:59], v10 offset:26624
	ds_read_b128 v[60:63], v10 offset:26880
	ds_read_b128 v[48:51], v10 offset:26112
	ds_read_b128 v[64:67], v10 offset:27136
	ds_read_b128 v[52:55], v10 offset:26368
	v_add_f32_dpp v80, v80, v80 row_mirror row_mask:0xf bank_mask:0xf bound_ctrl:1
	v_pk_fma_f32 v[4:5], v[80:81], v[84:85], v[76:77] op_sel_hi:[0,1,1]
	v_pk_fma_f32 v[6:7], v[80:81], v[86:87], v[78:79] op_sel_hi:[0,1,1]
	s_waitcnt lgkmcnt(12)
	v_pk_mul_f32 v[116:117], v[4:5], v[116:117]
	v_pk_fma_f32 v[116:117], v[6:7], v[118:119], v[116:117]
	v_add_f32_e32 v116, v116, v117
	v_pk_mul_f32 v[112:113], v[112:113], v[2:3] op_sel:[0,1] op_sel_hi:[1,1]
	v_pk_mul_f32 v[114:115], v[114:115], v[2:3] op_sel:[0,1] op_sel_hi:[1,1]
	v_add_f32_dpp v116, v116, v116 quad_perm:[1,0,3,2] row_mask:0xf bank_mask:0xf bound_ctrl:1
	v_pk_fma_f32 v[112:113], v[4:5], v[104:105], v[112:113]
	v_pk_fma_f32 v[114:115], v[6:7], v[106:107], v[114:115]
	v_add_f32_dpp v116, v116, v116 quad_perm:[2,3,0,1] row_mask:0xf bank_mask:0xf bound_ctrl:1
	v_pk_mul_f32 v[72:73], v[72:73], v[4:5]
	v_pk_fma_f32 v[72:73], v[6:7], v[74:75], v[72:73]
	v_add_f32_dpp v116, v116, v116 row_half_mirror row_mask:0xf bank_mask:0xf bound_ctrl:1
	v_add_f32_e32 v8, v72, v73
	ds_read_b128 v[76:79], v10 offset:28160
	ds_read2st64_b32 v[2:3], v11 offset0:113 offset1:119
	ds_read_b128 v[80:83], v10 offset:28416
	ds_read_b128 v[68:71], v10 offset:27648
	ds_read_b128 v[84:87], v10 offset:28672
	ds_read_b128 v[72:75], v10 offset:27904
	ds_write2st64_b32 v12, v9, v8 offset0:32 offset1:34
	v_add_f32_dpp v116, v116, v116 row_mirror row_mask:0xf bank_mask:0xf bound_ctrl:1
	v_pk_fma_f32 v[4:5], v[116:117], v[120:121], v[112:113] op_sel_hi:[0,1,1]
	v_pk_fma_f32 v[6:7], v[116:117], v[122:123], v[114:115] op_sel_hi:[0,1,1]
	s_waitcnt lgkmcnt(13)
	v_pk_mul_f32 v[40:41], v[4:5], v[40:41]
	v_pk_fma_f32 v[40:41], v[6:7], v[42:43], v[40:41]
	v_add_f32_e32 v40, v40, v41
	v_pk_mul_f32 v[36:37], v[36:37], v[0:1] op_sel_hi:[1,0]
	v_pk_mul_f32 v[38:39], v[38:39], v[0:1] op_sel_hi:[1,0]
	v_add_f32_dpp v40, v40, v40 quad_perm:[1,0,3,2] row_mask:0xf bank_mask:0xf bound_ctrl:1
	v_pk_fma_f32 v[36:37], v[4:5], v[28:29], v[36:37]
	v_pk_fma_f32 v[38:39], v[6:7], v[30:31], v[38:39]
	v_add_f32_dpp v40, v40, v40 quad_perm:[2,3,0,1] row_mask:0xf bank_mask:0xf bound_ctrl:1
	v_pk_mul_f32 v[108:109], v[108:109], v[4:5]
	v_pk_fma_f32 v[108:109], v[6:7], v[110:111], v[108:109]
	v_add_f32_dpp v40, v40, v40 row_half_mirror row_mask:0xf bank_mask:0xf bound_ctrl:1
	v_add_f32_e32 v9, v108, v109
	ds_read_b128 v[112:115], v10 offset:29696
	ds_read_b128 v[116:119], v10 offset:29952
	ds_read_b128 v[104:107], v10 offset:29184
	ds_read_b128 v[120:123], v10 offset:30208
	ds_read_b128 v[108:111], v10 offset:29440
	v_add_f32_dpp v40, v40, v40 row_mirror row_mask:0xf bank_mask:0xf bound_ctrl:1
	v_pk_fma_f32 v[4:5], v[40:41], v[44:45], v[36:37] op_sel_hi:[0,1,1]
	v_pk_fma_f32 v[6:7], v[40:41], v[46:47], v[38:39] op_sel_hi:[0,1,1]
	s_waitcnt lgkmcnt(12)
	v_pk_mul_f32 v[60:61], v[4:5], v[60:61]
	v_pk_fma_f32 v[60:61], v[6:7], v[62:63], v[60:61]
	v_add_f32_e32 v60, v60, v61
	v_pk_mul_f32 v[56:57], v[56:57], v[0:1] op_sel:[0,1] op_sel_hi:[1,1]
	v_pk_mul_f32 v[58:59], v[58:59], v[0:1] op_sel:[0,1] op_sel_hi:[1,1]
	v_add_f32_dpp v60, v60, v60 quad_perm:[1,0,3,2] row_mask:0xf bank_mask:0xf bound_ctrl:1
	v_pk_fma_f32 v[56:57], v[4:5], v[48:49], v[56:57]
	v_pk_fma_f32 v[58:59], v[6:7], v[50:51], v[58:59]
	v_add_f32_dpp v60, v60, v60 quad_perm:[2,3,0,1] row_mask:0xf bank_mask:0xf bound_ctrl:1
	v_pk_mul_f32 v[32:33], v[32:33], v[4:5]
	v_pk_fma_f32 v[32:33], v[6:7], v[34:35], v[32:33]
	v_add_f32_dpp v60, v60, v60 row_half_mirror row_mask:0xf bank_mask:0xf bound_ctrl:1
	v_add_f32_e32 v8, v32, v33
	ds_read_b128 v[36:39], v10 offset:31232
	ds_read2st64_b32 v[0:1], v11 offset0:125 offset1:131
	ds_read_b128 v[40:43], v10 offset:31488
	ds_read_b128 v[28:31], v10 offset:30720
	ds_read_b128 v[44:47], v10 offset:31744
	ds_read_b128 v[32:35], v10 offset:30976
	ds_write2st64_b32 v12, v9, v8 offset0:36 offset1:38
	v_add_f32_dpp v60, v60, v60 row_mirror row_mask:0xf bank_mask:0xf bound_ctrl:1
	v_pk_fma_f32 v[4:5], v[60:61], v[64:65], v[56:57] op_sel_hi:[0,1,1]
	v_pk_fma_f32 v[6:7], v[60:61], v[66:67], v[58:59] op_sel_hi:[0,1,1]
	s_waitcnt lgkmcnt(13)
	v_pk_mul_f32 v[80:81], v[4:5], v[80:81]
	v_pk_fma_f32 v[80:81], v[6:7], v[82:83], v[80:81]
	v_add_f32_e32 v80, v80, v81
	v_pk_mul_f32 v[76:77], v[76:77], v[2:3] op_sel_hi:[1,0]
	v_pk_mul_f32 v[78:79], v[78:79], v[2:3] op_sel_hi:[1,0]
	v_add_f32_dpp v80, v80, v80 quad_perm:[1,0,3,2] row_mask:0xf bank_mask:0xf bound_ctrl:1
	v_pk_fma_f32 v[76:77], v[4:5], v[68:69], v[76:77]
	v_pk_fma_f32 v[78:79], v[6:7], v[70:71], v[78:79]
	v_add_f32_dpp v80, v80, v80 quad_perm:[2,3,0,1] row_mask:0xf bank_mask:0xf bound_ctrl:1
	v_pk_mul_f32 v[52:53], v[52:53], v[4:5]
	v_pk_fma_f32 v[52:53], v[6:7], v[54:55], v[52:53]
	v_add_f32_dpp v80, v80, v80 row_half_mirror row_mask:0xf bank_mask:0xf bound_ctrl:1
	v_add_f32_e32 v9, v52, v53
	ds_read_b128 v[56:59], v10 offset:32768
	ds_read_b128 v[60:63], v10 offset:33024
	ds_read_b128 v[48:51], v10 offset:32256
	ds_read_b128 v[64:67], v10 offset:33280
	ds_read_b128 v[52:55], v10 offset:32512
	v_add_f32_dpp v80, v80, v80 row_mirror row_mask:0xf bank_mask:0xf bound_ctrl:1
	v_pk_fma_f32 v[4:5], v[80:81], v[84:85], v[76:77] op_sel_hi:[0,1,1]
	v_pk_fma_f32 v[6:7], v[80:81], v[86:87], v[78:79] op_sel_hi:[0,1,1]
	s_waitcnt lgkmcnt(12)
	v_pk_mul_f32 v[116:117], v[4:5], v[116:117]
	v_pk_fma_f32 v[116:117], v[6:7], v[118:119], v[116:117]
	v_add_f32_e32 v116, v116, v117
	v_pk_mul_f32 v[112:113], v[112:113], v[2:3] op_sel:[0,1] op_sel_hi:[1,1]
	v_pk_mul_f32 v[114:115], v[114:115], v[2:3] op_sel:[0,1] op_sel_hi:[1,1]
	v_add_f32_dpp v116, v116, v116 quad_perm:[1,0,3,2] row_mask:0xf bank_mask:0xf bound_ctrl:1
	v_pk_fma_f32 v[112:113], v[4:5], v[104:105], v[112:113]
	v_pk_fma_f32 v[114:115], v[6:7], v[106:107], v[114:115]
	v_add_f32_dpp v116, v116, v116 quad_perm:[2,3,0,1] row_mask:0xf bank_mask:0xf bound_ctrl:1
	v_pk_mul_f32 v[72:73], v[72:73], v[4:5]
	v_pk_fma_f32 v[72:73], v[6:7], v[74:75], v[72:73]
	v_add_f32_dpp v116, v116, v116 row_half_mirror row_mask:0xf bank_mask:0xf bound_ctrl:1
	v_add_f32_e32 v8, v72, v73
	ds_read_b128 v[76:79], v10 offset:34304
	ds_read2st64_b32 v[2:3], v11 offset0:137 offset1:143
	ds_read_b128 v[80:83], v10 offset:34560
	ds_read_b128 v[68:71], v10 offset:33792
	ds_read_b128 v[84:87], v10 offset:34816
	ds_read_b128 v[72:75], v10 offset:34048
	ds_write2st64_b32 v12, v9, v8 offset0:40 offset1:42
	v_add_f32_dpp v116, v116, v116 row_mirror row_mask:0xf bank_mask:0xf bound_ctrl:1
	v_pk_fma_f32 v[4:5], v[116:117], v[120:121], v[112:113] op_sel_hi:[0,1,1]
	v_pk_fma_f32 v[6:7], v[116:117], v[122:123], v[114:115] op_sel_hi:[0,1,1]
	s_waitcnt lgkmcnt(13)
	v_pk_mul_f32 v[40:41], v[4:5], v[40:41]
	v_pk_fma_f32 v[40:41], v[6:7], v[42:43], v[40:41]
	v_add_f32_e32 v40, v40, v41
	v_pk_mul_f32 v[36:37], v[36:37], v[0:1] op_sel_hi:[1,0]
	v_pk_mul_f32 v[38:39], v[38:39], v[0:1] op_sel_hi:[1,0]
	v_add_f32_dpp v40, v40, v40 quad_perm:[1,0,3,2] row_mask:0xf bank_mask:0xf bound_ctrl:1
	v_pk_fma_f32 v[36:37], v[4:5], v[28:29], v[36:37]
	v_pk_fma_f32 v[38:39], v[6:7], v[30:31], v[38:39]
	v_add_f32_dpp v40, v40, v40 quad_perm:[2,3,0,1] row_mask:0xf bank_mask:0xf bound_ctrl:1
	v_pk_mul_f32 v[108:109], v[108:109], v[4:5]
	v_pk_fma_f32 v[108:109], v[6:7], v[110:111], v[108:109]
	v_add_f32_dpp v40, v40, v40 row_half_mirror row_mask:0xf bank_mask:0xf bound_ctrl:1
	v_add_f32_e32 v9, v108, v109
	ds_read_b128 v[112:115], v10 offset:35840
	ds_read_b128 v[116:119], v10 offset:36096
	ds_read_b128 v[104:107], v10 offset:35328
	ds_read_b128 v[120:123], v10 offset:36352
	ds_read_b128 v[108:111], v10 offset:35584
	v_add_f32_dpp v40, v40, v40 row_mirror row_mask:0xf bank_mask:0xf bound_ctrl:1
	v_pk_fma_f32 v[4:5], v[40:41], v[44:45], v[36:37] op_sel_hi:[0,1,1]
	v_pk_fma_f32 v[6:7], v[40:41], v[46:47], v[38:39] op_sel_hi:[0,1,1]
	s_waitcnt lgkmcnt(12)
	v_pk_mul_f32 v[60:61], v[4:5], v[60:61]
	v_pk_fma_f32 v[60:61], v[6:7], v[62:63], v[60:61]
	v_add_f32_e32 v60, v60, v61
	v_pk_mul_f32 v[56:57], v[56:57], v[0:1] op_sel:[0,1] op_sel_hi:[1,1]
	v_pk_mul_f32 v[58:59], v[58:59], v[0:1] op_sel:[0,1] op_sel_hi:[1,1]
	v_add_f32_dpp v60, v60, v60 quad_perm:[1,0,3,2] row_mask:0xf bank_mask:0xf bound_ctrl:1
	v_pk_fma_f32 v[56:57], v[4:5], v[48:49], v[56:57]
	v_pk_fma_f32 v[58:59], v[6:7], v[50:51], v[58:59]
	v_add_f32_dpp v60, v60, v60 quad_perm:[2,3,0,1] row_mask:0xf bank_mask:0xf bound_ctrl:1
	v_pk_mul_f32 v[32:33], v[32:33], v[4:5]
	v_pk_fma_f32 v[32:33], v[6:7], v[34:35], v[32:33]
	v_add_f32_dpp v60, v60, v60 row_half_mirror row_mask:0xf bank_mask:0xf bound_ctrl:1
	v_add_f32_e32 v8, v32, v33
	ds_read_b128 v[36:39], v10 offset:37376
	ds_read2st64_b32 v[0:1], v11 offset0:149 offset1:155
	ds_read_b128 v[40:43], v10 offset:37632
	ds_read_b128 v[28:31], v10 offset:36864
	ds_read_b128 v[44:47], v10 offset:37888
	ds_read_b128 v[32:35], v10 offset:37120
	ds_write2st64_b32 v12, v9, v8 offset0:44 offset1:46
	v_add_f32_dpp v60, v60, v60 row_mirror row_mask:0xf bank_mask:0xf bound_ctrl:1
	v_pk_fma_f32 v[4:5], v[60:61], v[64:65], v[56:57] op_sel_hi:[0,1,1]
	v_pk_fma_f32 v[6:7], v[60:61], v[66:67], v[58:59] op_sel_hi:[0,1,1]
	s_waitcnt lgkmcnt(13)
	v_pk_mul_f32 v[80:81], v[4:5], v[80:81]
	v_pk_fma_f32 v[80:81], v[6:7], v[82:83], v[80:81]
	v_add_f32_e32 v80, v80, v81
	v_pk_mul_f32 v[76:77], v[76:77], v[2:3] op_sel_hi:[1,0]
	v_pk_mul_f32 v[78:79], v[78:79], v[2:3] op_sel_hi:[1,0]
	v_add_f32_dpp v80, v80, v80 quad_perm:[1,0,3,2] row_mask:0xf bank_mask:0xf bound_ctrl:1
	v_pk_fma_f32 v[76:77], v[4:5], v[68:69], v[76:77]
	v_pk_fma_f32 v[78:79], v[6:7], v[70:71], v[78:79]
	v_add_f32_dpp v80, v80, v80 quad_perm:[2,3,0,1] row_mask:0xf bank_mask:0xf bound_ctrl:1
	v_pk_mul_f32 v[52:53], v[52:53], v[4:5]
	v_pk_fma_f32 v[52:53], v[6:7], v[54:55], v[52:53]
	v_add_f32_dpp v80, v80, v80 row_half_mirror row_mask:0xf bank_mask:0xf bound_ctrl:1
	v_add_f32_e32 v9, v52, v53
	ds_read_b128 v[56:59], v10 offset:38912
	ds_read_b128 v[60:63], v10 offset:39168
	ds_read_b128 v[48:51], v10 offset:38400
	ds_read_b128 v[64:67], v10 offset:39424
	ds_read_b128 v[52:55], v10 offset:38656
	v_add_f32_dpp v80, v80, v80 row_mirror row_mask:0xf bank_mask:0xf bound_ctrl:1
	v_pk_fma_f32 v[4:5], v[80:81], v[84:85], v[76:77] op_sel_hi:[0,1,1]
	v_pk_fma_f32 v[6:7], v[80:81], v[86:87], v[78:79] op_sel_hi:[0,1,1]
	s_waitcnt lgkmcnt(12)
	v_pk_mul_f32 v[116:117], v[4:5], v[116:117]
	v_pk_fma_f32 v[116:117], v[6:7], v[118:119], v[116:117]
	v_add_f32_e32 v116, v116, v117
	v_pk_mul_f32 v[112:113], v[112:113], v[2:3] op_sel:[0,1] op_sel_hi:[1,1]
	v_pk_mul_f32 v[114:115], v[114:115], v[2:3] op_sel:[0,1] op_sel_hi:[1,1]
	v_add_f32_dpp v116, v116, v116 quad_perm:[1,0,3,2] row_mask:0xf bank_mask:0xf bound_ctrl:1
	v_pk_fma_f32 v[112:113], v[4:5], v[104:105], v[112:113]
	v_pk_fma_f32 v[114:115], v[6:7], v[106:107], v[114:115]
	v_add_f32_dpp v116, v116, v116 quad_perm:[2,3,0,1] row_mask:0xf bank_mask:0xf bound_ctrl:1
	v_pk_mul_f32 v[72:73], v[72:73], v[4:5]
	v_pk_fma_f32 v[72:73], v[6:7], v[74:75], v[72:73]
	v_add_f32_dpp v116, v116, v116 row_half_mirror row_mask:0xf bank_mask:0xf bound_ctrl:1
	v_add_f32_e32 v8, v72, v73
	ds_read_b128 v[76:79], v10 offset:40448
	ds_read2st64_b32 v[2:3], v11 offset0:161 offset1:167
	ds_read_b128 v[80:83], v10 offset:40704
	ds_read_b128 v[68:71], v10 offset:39936
	ds_read_b128 v[84:87], v10 offset:40960
	ds_read_b128 v[72:75], v10 offset:40192
	ds_write2st64_b32 v12, v9, v8 offset0:48 offset1:50
	v_add_f32_dpp v116, v116, v116 row_mirror row_mask:0xf bank_mask:0xf bound_ctrl:1
	v_pk_fma_f32 v[4:5], v[116:117], v[120:121], v[112:113] op_sel_hi:[0,1,1]
	v_pk_fma_f32 v[6:7], v[116:117], v[122:123], v[114:115] op_sel_hi:[0,1,1]
	s_waitcnt lgkmcnt(13)
	v_pk_mul_f32 v[40:41], v[4:5], v[40:41]
	v_pk_fma_f32 v[40:41], v[6:7], v[42:43], v[40:41]
	v_add_f32_e32 v40, v40, v41
	v_pk_mul_f32 v[36:37], v[36:37], v[0:1] op_sel_hi:[1,0]
	v_pk_mul_f32 v[38:39], v[38:39], v[0:1] op_sel_hi:[1,0]
	v_add_f32_dpp v40, v40, v40 quad_perm:[1,0,3,2] row_mask:0xf bank_mask:0xf bound_ctrl:1
	v_pk_fma_f32 v[36:37], v[4:5], v[28:29], v[36:37]
	v_pk_fma_f32 v[38:39], v[6:7], v[30:31], v[38:39]
	v_add_f32_dpp v40, v40, v40 quad_perm:[2,3,0,1] row_mask:0xf bank_mask:0xf bound_ctrl:1
	v_pk_mul_f32 v[108:109], v[108:109], v[4:5]
	v_pk_fma_f32 v[108:109], v[6:7], v[110:111], v[108:109]
	v_add_f32_dpp v40, v40, v40 row_half_mirror row_mask:0xf bank_mask:0xf bound_ctrl:1
	v_add_f32_e32 v9, v108, v109
	ds_read_b128 v[112:115], v10 offset:41984
	ds_read_b128 v[116:119], v10 offset:42240
	ds_read_b128 v[104:107], v10 offset:41472
	ds_read_b128 v[120:123], v10 offset:42496
	ds_read_b128 v[108:111], v10 offset:41728
	v_add_f32_dpp v40, v40, v40 row_mirror row_mask:0xf bank_mask:0xf bound_ctrl:1
	v_pk_fma_f32 v[4:5], v[40:41], v[44:45], v[36:37] op_sel_hi:[0,1,1]
	v_pk_fma_f32 v[6:7], v[40:41], v[46:47], v[38:39] op_sel_hi:[0,1,1]
	s_waitcnt lgkmcnt(12)
	v_pk_mul_f32 v[60:61], v[4:5], v[60:61]
	v_pk_fma_f32 v[60:61], v[6:7], v[62:63], v[60:61]
	v_add_f32_e32 v60, v60, v61
	v_pk_mul_f32 v[56:57], v[56:57], v[0:1] op_sel:[0,1] op_sel_hi:[1,1]
	v_pk_mul_f32 v[58:59], v[58:59], v[0:1] op_sel:[0,1] op_sel_hi:[1,1]
	v_add_f32_dpp v60, v60, v60 quad_perm:[1,0,3,2] row_mask:0xf bank_mask:0xf bound_ctrl:1
	v_pk_fma_f32 v[56:57], v[4:5], v[48:49], v[56:57]
	v_pk_fma_f32 v[58:59], v[6:7], v[50:51], v[58:59]
	v_add_f32_dpp v60, v60, v60 quad_perm:[2,3,0,1] row_mask:0xf bank_mask:0xf bound_ctrl:1
	v_pk_mul_f32 v[32:33], v[32:33], v[4:5]
	v_pk_fma_f32 v[32:33], v[6:7], v[34:35], v[32:33]
	v_add_f32_dpp v60, v60, v60 row_half_mirror row_mask:0xf bank_mask:0xf bound_ctrl:1
	v_add_f32_e32 v8, v32, v33
	ds_read_b128 v[36:39], v10 offset:43520
	ds_read2st64_b32 v[0:1], v11 offset0:173 offset1:179
	ds_read_b128 v[40:43], v10 offset:43776
	ds_read_b128 v[28:31], v10 offset:43008
	ds_read_b128 v[44:47], v10 offset:44032
	ds_read_b128 v[32:35], v10 offset:43264
	ds_write2st64_b32 v12, v9, v8 offset0:52 offset1:54
	v_add_f32_dpp v60, v60, v60 row_mirror row_mask:0xf bank_mask:0xf bound_ctrl:1
	v_pk_fma_f32 v[4:5], v[60:61], v[64:65], v[56:57] op_sel_hi:[0,1,1]
	v_pk_fma_f32 v[6:7], v[60:61], v[66:67], v[58:59] op_sel_hi:[0,1,1]
	s_waitcnt lgkmcnt(13)
	v_pk_mul_f32 v[80:81], v[4:5], v[80:81]
	v_pk_fma_f32 v[80:81], v[6:7], v[82:83], v[80:81]
	v_add_f32_e32 v80, v80, v81
	v_pk_mul_f32 v[76:77], v[76:77], v[2:3] op_sel_hi:[1,0]
	v_pk_mul_f32 v[78:79], v[78:79], v[2:3] op_sel_hi:[1,0]
	v_add_f32_dpp v80, v80, v80 quad_perm:[1,0,3,2] row_mask:0xf bank_mask:0xf bound_ctrl:1
	v_pk_fma_f32 v[76:77], v[4:5], v[68:69], v[76:77]
	v_pk_fma_f32 v[78:79], v[6:7], v[70:71], v[78:79]
	v_add_f32_dpp v80, v80, v80 quad_perm:[2,3,0,1] row_mask:0xf bank_mask:0xf bound_ctrl:1
	v_pk_mul_f32 v[52:53], v[52:53], v[4:5]
	v_pk_fma_f32 v[52:53], v[6:7], v[54:55], v[52:53]
	v_add_f32_dpp v80, v80, v80 row_half_mirror row_mask:0xf bank_mask:0xf bound_ctrl:1
	v_add_f32_e32 v9, v52, v53
	ds_read_b128 v[56:59], v10 offset:45056
	ds_read_b128 v[60:63], v10 offset:45312
	ds_read_b128 v[48:51], v10 offset:44544
	ds_read_b128 v[64:67], v10 offset:45568
	ds_read_b128 v[52:55], v10 offset:44800
	v_add_f32_dpp v80, v80, v80 row_mirror row_mask:0xf bank_mask:0xf bound_ctrl:1
	v_pk_fma_f32 v[4:5], v[80:81], v[84:85], v[76:77] op_sel_hi:[0,1,1]
	v_pk_fma_f32 v[6:7], v[80:81], v[86:87], v[78:79] op_sel_hi:[0,1,1]
	s_waitcnt lgkmcnt(12)
	v_pk_mul_f32 v[116:117], v[4:5], v[116:117]
	v_pk_fma_f32 v[116:117], v[6:7], v[118:119], v[116:117]
	v_add_f32_e32 v116, v116, v117
	v_pk_mul_f32 v[112:113], v[112:113], v[2:3] op_sel:[0,1] op_sel_hi:[1,1]
	v_pk_mul_f32 v[114:115], v[114:115], v[2:3] op_sel:[0,1] op_sel_hi:[1,1]
	v_add_f32_dpp v116, v116, v116 quad_perm:[1,0,3,2] row_mask:0xf bank_mask:0xf bound_ctrl:1
	v_pk_fma_f32 v[112:113], v[4:5], v[104:105], v[112:113]
	v_pk_fma_f32 v[114:115], v[6:7], v[106:107], v[114:115]
	v_add_f32_dpp v116, v116, v116 quad_perm:[2,3,0,1] row_mask:0xf bank_mask:0xf bound_ctrl:1
	v_pk_mul_f32 v[72:73], v[72:73], v[4:5]
	v_pk_fma_f32 v[72:73], v[6:7], v[74:75], v[72:73]
	v_add_f32_dpp v116, v116, v116 row_half_mirror row_mask:0xf bank_mask:0xf bound_ctrl:1
	v_add_f32_e32 v8, v72, v73
	ds_read_b128 v[76:79], v10 offset:46592
	ds_read2st64_b32 v[2:3], v11 offset0:185 offset1:191
	ds_read_b128 v[80:83], v10 offset:46848
	ds_read_b128 v[68:71], v10 offset:46080
	ds_read_b128 v[84:87], v10 offset:47104
	ds_read_b128 v[72:75], v10 offset:46336
	ds_write2st64_b32 v12, v9, v8 offset0:56 offset1:58
	v_add_f32_dpp v116, v116, v116 row_mirror row_mask:0xf bank_mask:0xf bound_ctrl:1
	v_pk_fma_f32 v[4:5], v[116:117], v[120:121], v[112:113] op_sel_hi:[0,1,1]
	v_pk_fma_f32 v[6:7], v[116:117], v[122:123], v[114:115] op_sel_hi:[0,1,1]
	s_waitcnt lgkmcnt(13)
	v_pk_mul_f32 v[40:41], v[4:5], v[40:41]
	v_pk_fma_f32 v[40:41], v[6:7], v[42:43], v[40:41]
	v_add_f32_e32 v40, v40, v41
	v_pk_mul_f32 v[36:37], v[36:37], v[0:1] op_sel_hi:[1,0]
	v_pk_mul_f32 v[38:39], v[38:39], v[0:1] op_sel_hi:[1,0]
	v_add_f32_dpp v40, v40, v40 quad_perm:[1,0,3,2] row_mask:0xf bank_mask:0xf bound_ctrl:1
	v_pk_fma_f32 v[36:37], v[4:5], v[28:29], v[36:37]
	v_pk_fma_f32 v[38:39], v[6:7], v[30:31], v[38:39]
	v_add_f32_dpp v40, v40, v40 quad_perm:[2,3,0,1] row_mask:0xf bank_mask:0xf bound_ctrl:1
	v_pk_mul_f32 v[108:109], v[108:109], v[4:5]
	v_pk_fma_f32 v[108:109], v[6:7], v[110:111], v[108:109]
	v_add_f32_dpp v40, v40, v40 row_half_mirror row_mask:0xf bank_mask:0xf bound_ctrl:1
	v_add_f32_e32 v9, v108, v109
	ds_read_b128 v[112:115], v10 offset:48128
	ds_read_b128 v[116:119], v10 offset:48384
	ds_read_b128 v[104:107], v10 offset:47616
	ds_read_b128 v[120:123], v10 offset:48640
	ds_read_b128 v[108:111], v10 offset:47872
	v_add_f32_dpp v40, v40, v40 row_mirror row_mask:0xf bank_mask:0xf bound_ctrl:1
	v_pk_fma_f32 v[4:5], v[40:41], v[44:45], v[36:37] op_sel_hi:[0,1,1]
	v_pk_fma_f32 v[6:7], v[40:41], v[46:47], v[38:39] op_sel_hi:[0,1,1]
	s_waitcnt lgkmcnt(12)
	v_pk_mul_f32 v[60:61], v[4:5], v[60:61]
	v_pk_fma_f32 v[60:61], v[6:7], v[62:63], v[60:61]
	v_add_f32_e32 v60, v60, v61
	v_pk_mul_f32 v[56:57], v[56:57], v[0:1] op_sel:[0,1] op_sel_hi:[1,1]
	v_pk_mul_f32 v[58:59], v[58:59], v[0:1] op_sel:[0,1] op_sel_hi:[1,1]
	v_add_f32_dpp v60, v60, v60 quad_perm:[1,0,3,2] row_mask:0xf bank_mask:0xf bound_ctrl:1
	v_pk_fma_f32 v[56:57], v[4:5], v[48:49], v[56:57]
	v_pk_fma_f32 v[58:59], v[6:7], v[50:51], v[58:59]
	v_add_f32_dpp v60, v60, v60 quad_perm:[2,3,0,1] row_mask:0xf bank_mask:0xf bound_ctrl:1
	v_pk_mul_f32 v[32:33], v[32:33], v[4:5]
	v_pk_fma_f32 v[32:33], v[6:7], v[34:35], v[32:33]
	v_add_f32_dpp v60, v60, v60 row_half_mirror row_mask:0xf bank_mask:0xf bound_ctrl:1
	v_add_f32_e32 v8, v32, v33
	ds_write2st64_b32 v12, v9, v8 offset0:60 offset1:62
	s_nop 0
	v_add_f32_dpp v60, v60, v60 row_mirror row_mask:0xf bank_mask:0xf bound_ctrl:1
	s_andn2_b32 s0, 1, s54
	s_mul_i32 s1, s0, 0xc000
	s_lshl_b32 s4, s30, 2
	v_add_u32_e32 v10, s1, v97
	s_add_i32 s1, s1, s4
	v_lshl_add_u32 v11, v95, 2, s1
	v_lshl_add_u32 v12, s0, 14, v102
